# E3 row loop: the row-invariant gate / post-norm / pre-norm / shift / scale vectors loaded once before the loop into idle registers (they were re-loaded per row, each behind a vmcnt(0) that also waited
# speedup vs baseline: 1.0117x; 1.0069x over previous
.LBB0_322:
	s_nop 0
	v_readlane_b32 s2, v255, 50
	v_readlane_b32 s3, v255, 51
	s_and_b64 vcc, exec, s[2:3]
	s_cbranch_vccz .LBB0_329
	v_mbcnt_lo_u32_b32 v0, -1, 0
	v_mbcnt_hi_u32_b32 v0, -1, v0
	v_readlane_b32 s2, v253, 29
	v_or_b32_e32 v0, s55, v0
	v_ashrrev_i32_e32 v1, 6, v0
	s_waitcnt vmcnt(0)
	v_add_u32_e32 v16, s2, v1
	s_movk_i32 s2, 0x4000
	v_cmp_gt_i32_e32 vcc, s2, v16
	v_mbcnt_lo_u32_b32 v0, -1, 0
	v_mbcnt_hi_u32_b32 v0, -1, v0
	s_and_saveexec_b64 s[2:3], vcc
	s_cbranch_execz .LBB0_328
	v_readlane_b32 s4, v255, 47
	v_readlane_b32 s5, v255, 48
	s_mov_b32 s12, s4
	s_lshl_b32 s4, s4, 10
	s_ashr_i32 s5, s4, 31
	v_readlane_b32 s36, v255, 5
	s_lshl_b64 s[8:9], s[4:5], 2
	v_readlane_b32 s48, v255, 17
	v_readlane_b32 s49, v255, 18
	s_add_u32 s10, s48, s8
	s_mulk_i32 s12, 0xc00
	s_addc_u32 s11, s49, s9
	s_ashr_i32 s13, s12, 31
	s_lshl_b64 s[8:9], s[12:13], 2
	v_readlane_b32 s34, v253, 30
	v_readlane_b32 s35, v253, 31
	s_add_u32 s5, s34, s8
	s_addc_u32 s8, s35, s9
	v_readlane_b32 s16, v253, 6
	s_add_u32 s14, s5, 0x2000
	v_readlane_b32 s13, v255, 46
	v_readlane_b32 s17, v253, 7
	s_addc_u32 s15, s8, 0
	s_add_i32 s5, s13, 4
	v_ashrrev_i32_e32 v17, 31, v16
	v_readlane_b32 s16, v253, 47
	v_readlane_b32 s37, v255, 6
	s_cmp_lt_u32 s5, 13
	v_readlane_b32 s28, v253, 18
	v_readlane_b32 s29, v253, 19
	v_lshlrev_b64 v[2:3], 12, v[16:17]
	v_readlane_b32 s17, v253, 48
	v_lshlrev_b32_e32 v1, 4, v0
	s_cselect_b32 s9, s37, s29
	s_cselect_b32 s8, s36, s28
	v_lshl_add_u64 v[4:5], s[16:17], 0, v[2:3]
	v_and_b32_e32 v40, 0x3f0, v1
	v_lshl_add_u64 v[4:5], v[4:5], 0, v[40:41]
	v_lshl_add_u64 v[6:7], s[8:9], 0, v[2:3]
	v_lshl_add_u64 v[6:7], v[6:7], 0, v[40:41]
	global_load_dwordx4 v[50:53], v[4:5], off
	global_load_dwordx4 v[62:65], v[4:5], off offset:1024
	global_load_dwordx4 v[54:57], v[6:7], off
	global_load_dwordx4 v[58:61], v[6:7], off offset:1024
	global_load_dwordx4 v[66:69], v[4:5], off offset:2048
	global_load_dwordx4 v[84:87], v[4:5], off offset:3072
	global_load_dwordx4 v[70:73], v[6:7], off offset:2048
	global_load_dwordx4 v[74:77], v[6:7], off offset:3072
	s_cmp_lt_i32 s13, 23
	v_lshl_add_u64 v[20:21], s[8:9], 0, v[40:41]
	s_cselect_b64 s[8:9], -1, 0
	s_addk_i32 s12, 0xc00
	s_addk_i32 s4, 0x400
	s_ashr_i32 s13, s12, 31
	s_ashr_i32 s5, s4, 31
	s_lshl_b64 s[12:13], s[12:13], 2
	s_add_u32 s12, s34, s12
	s_addc_u32 s13, s35, s13
	v_lshl_add_u64 v[18:19], s[16:17], 0, v[40:41]
	s_add_u32 s16, s12, 0x1000
	v_readlane_b32 s46, v255, 15
	s_addc_u32 s17, s13, 0
	s_lshl_b64 s[4:5], s[4:5], 2
	v_readlane_b32 s47, v255, 16
	v_or_b32_e32 v4, 0x400, v40
	v_mov_b32_e32 v5, v41
	s_add_u32 s4, s46, s4
	v_lshl_add_u64 v[26:27], s[16:17], 0, v[4:5]
	v_lshl_add_u64 v[36:37], s[14:15], 0, v[4:5]
	s_addc_u32 s5, s47, s5
	v_and_b32_e32 v4, 63, v0
	v_lshl_add_u64 v[22:23], s[12:13], 0, v[40:41]
	v_lshl_add_u64 v[24:25], s[16:17], 0, v[40:41]
	v_or_b32_e32 v6, 0x800, v40
	v_or_b32_e32 v8, 0xc00, v40
	v_lshl_add_u64 v[32:33], s[14:15], 0, v[40:41]
	v_lshl_add_u64 v[34:35], s[10:11], 0, v[40:41]
	v_lshl_add_u64 v[44:45], s[4:5], 0, v[40:41]
	v_lshlrev_b32_e32 v40, 3, v4
	v_mad_i64_i32 v[0:1], s[4:5], v16, s33, v[40:41]
	v_readlane_b32 s4, v253, 27
	v_mov_b32_e32 v7, v41
	v_mov_b32_e32 v9, v41
	v_readlane_b32 s5, v253, 28
	v_lshl_or_b32 v2, v4, 4, v2
	v_lshl_add_u64 v[28:29], s[16:17], 0, v[6:7]
	v_lshl_add_u64 v[30:31], s[16:17], 0, v[8:9]
	v_lshl_add_u64 v[38:39], s[14:15], 0, v[6:7]
	v_lshl_add_u64 v[42:43], s[14:15], 0, v[8:9]
	v_lshl_add_u64 v[46:47], s[4:5], 0, v[0:1]
	v_lshl_add_u64 v[48:49], s[28:29], 0, v[2:3]
	s_mov_b64 s[10:11], 0
	v_readlane_b32 s38, v255, 7
	v_readlane_b32 s39, v255, 8
	v_readlane_b32 s40, v255, 9
	v_readlane_b32 s41, v255, 10
	v_readlane_b32 s42, v255, 11
	v_readlane_b32 s43, v255, 12
	v_readlane_b32 s44, v255, 13
	v_readlane_b32 s45, v255, 14
	v_readlane_b32 s50, v255, 19
	v_readlane_b32 s51, v255, 20
	v_readlane_b32 s18, v253, 8
	v_readlane_b32 s19, v253, 9
	v_readlane_b32 s20, v253, 10
	v_readlane_b32 s21, v253, 11
	v_readlane_b32 s22, v253, 12
	v_readlane_b32 s23, v253, 13
	v_readlane_b32 s24, v253, 14
	v_readlane_b32 s25, v253, 15
	v_readlane_b32 s26, v253, 16
	v_readlane_b32 s27, v253, 17
	v_readlane_b32 s30, v253, 20
	v_readlane_b32 s31, v253, 21
	global_load_dwordx4 v[112:115], v[34:35], off
	global_load_dwordx4 v[116:119], v[32:33], off
	global_load_dwordx4 v[120:123], v[34:35], off offset:1024
	global_load_dwordx4 v[124:127], v[36:37], off
	global_load_dwordx4 v[128:131], v[34:35], off offset:2048
	global_load_dwordx4 v[132:135], v[38:39], off
	global_load_dwordx4 v[136:139], v[34:35], off offset:3072
	global_load_dwordx4 v[140:143], v[42:43], off
	global_load_dwordx4 v[144:147], v[44:45], off
	global_load_dwordx4 v[148:151], v[22:23], off
	global_load_dwordx4 v[152:155], v[24:25], off
	global_load_dwordx4 v[156:159], v[44:45], off offset:1024
	global_load_dwordx4 v[160:163], v[22:23], off offset:1024
	global_load_dwordx4 v[164:167], v[26:27], off
	global_load_dwordx4 v[168:171], v[44:45], off offset:2048
	global_load_dwordx4 v[172:175], v[22:23], off offset:2048
	global_load_dwordx4 v[176:179], v[28:29], off
	global_load_dwordx4 v[180:183], v[44:45], off offset:3072
	global_load_dwordx4 v[184:187], v[22:23], off offset:3072
	global_load_dwordx4 v[188:191], v[30:31], off
	s_waitcnt vmcnt(0)
	s_branch .LBB0_326

.LBB0_326:
	s_waitcnt vmcnt(4)
	v_mov_b64_e32 v[0:1], v[112:113]
	v_mov_b64_e32 v[2:3], v[114:115]
	v_mov_b64_e32 v[4:5], v[116:117]
	v_mov_b64_e32 v[6:7], v[118:119]
	v_mov_b64_e32 v[12:13], v[50:51]
	v_mul_f32_e32 v40, v13, v13
	v_mov_b64_e32 v[14:15], v[52:53]
	v_fmac_f32_e32 v40, v12, v12
	v_fmac_f32_e32 v40, v14, v14
	v_mov_b64_e32 v[8:9], v[62:63]
	v_fmac_f32_e32 v40, v15, v15
	v_fmac_f32_e32 v40, v8, v8
	v_mov_b64_e32 v[10:11], v[64:65]
	v_fmac_f32_e32 v40, v9, v9
	v_mov_b64_e32 v[94:95], v[68:69]
	v_fmac_f32_e32 v40, v10, v10
	v_mov_b64_e32 v[92:93], v[66:67]
	v_mov_b32_e32 v17, v16
	v_fmac_f32_e32 v40, v11, v11
	v_add_u32_e32 v16, s60, v17
	s_movk_i32 s4, 0x4000
	v_fmac_f32_e32 v40, v92, v92
	v_mov_b64_e32 v[90:91], v[86:87]
	v_pk_mul_f32 v[66:67], v[94:95], v[94:95]
	v_cmp_gt_i32_e32 vcc, s4, v16
	v_fmac_f32_e32 v40, v93, v93
	v_mov_b64_e32 v[88:89], v[84:85]
	v_mov_b64_e32 v[102:103], v[72:73]
	v_cndmask_b32_e32 v50, v17, v16, vcc
	v_add_f32_e32 v17, v66, v40
	v_mov_b64_e32 v[100:101], v[70:71]
	v_pk_mul_f32 v[70:71], v[88:89], v[88:89]
	v_add_f32_e32 v17, v67, v17
	v_add_f32_e32 v17, v70, v17
	v_pk_mul_f32 v[68:69], v[90:91], v[90:91]
	v_add_f32_e32 v17, v71, v17
	v_add_f32_e32 v17, v68, v17
	v_add_f32_e32 v17, v69, v17
	v_mov_b32_e32 v40, 0x358637bd
	v_mov_b64_e32 v[110:111], v[56:57]
	v_add_f32_dpp v17, v17, v17 quad_perm:[1,0,3,2] row_mask:0xf bank_mask:0xf bound_ctrl:1
	v_ashrrev_i32_e32 v51, 31, v50
	v_mov_b64_e32 v[98:99], v[76:77]
	v_add_f32_dpp v17, v17, v17 quad_perm:[2,3,0,1] row_mask:0xf bank_mask:0xf bound_ctrl:1
	v_mov_b64_e32 v[108:109], v[54:55]
	v_lshlrev_b64 v[50:51], 12, v[50:51]
	v_add_f32_dpp v17, v17, v17 row_half_mirror row_mask:0xf bank_mask:0xf bound_ctrl:1
	v_mov_b64_e32 v[96:97], v[74:75]
	v_mov_b64_e32 v[106:107], v[60:61]
	v_add_f32_dpp v17, v17, v17 row_mirror row_mask:0xf bank_mask:0xf bound_ctrl:1
	v_lshl_add_u64 v[72:73], v[18:19], 0, v[50:51]
	v_readlane_b32 s12, v17, 16
	v_readlane_b32 s13, v17, 48
	v_readlane_b32 s4, v17, 0
	v_readlane_b32 s5, v17, 32
	v_mov_b32_e32 v66, s12
	v_mov_b32_e32 v67, s13
	v_pk_add_f32 v[66:67], s[4:5], v[66:67]
	v_lshl_add_u64 v[74:75], v[20:21], 0, v[50:51]
	v_add_f32_e32 v17, v66, v67
	v_fmamk_f32 v17, v17, 0x3a800000, v40
	v_mul_f32_e32 v40, 0x4b800000, v17
	v_cmp_gt_f32_e32 vcc, s70, v17
	v_mov_b64_e32 v[104:105], v[58:59]
	global_load_dwordx4 v[50:53], v[72:73], off
	global_load_dwordx4 v[62:65], v[72:73], off offset:1024
	global_load_dwordx4 v[54:57], v[74:75], off
	global_load_dwordx4 v[58:61], v[74:75], off offset:1024
	v_cndmask_b32_e32 v17, v17, v40, vcc
	v_rsq_f32_e32 v17, v17
	global_load_dwordx4 v[66:69], v[72:73], off offset:2048
	global_load_dwordx4 v[84:87], v[72:73], off offset:3072
	s_nop 0
	global_load_dwordx4 v[70:73], v[74:75], off offset:2048
	s_nop 0
	global_load_dwordx4 v[74:77], v[74:75], off offset:3072
	v_cmp_lt_i32_e64 s[4:5], s66, v16
	v_mul_f32_e32 v40, 0x45800000, v17
	v_cndmask_b32_e32 v40, v17, v40, vcc
	v_pk_mul_f32 v[12:13], v[12:13], v[40:41] op_sel_hi:[1,0]
	v_pk_mul_f32 v[14:15], v[14:15], v[40:41] op_sel_hi:[1,0]
	v_pk_mul_f32 v[8:9], v[8:9], v[40:41] op_sel_hi:[1,0]
	v_pk_mul_f32 v[10:11], v[10:11], v[40:41] op_sel_hi:[1,0]
	v_pk_mul_f32 v[78:79], v[92:93], v[40:41] op_sel_hi:[1,0]
	v_pk_mul_f32 v[92:93], v[94:95], v[40:41] op_sel_hi:[1,0]
	s_andn2_b64 vcc, exec, s[8:9]
	v_pk_mul_f32 v[0:1], v[0:1], v[12:13]
	v_pk_mul_f32 v[2:3], v[2:3], v[14:15]
	v_pk_fma_f32 v[12:13], v[4:5], v[0:1], v[108:109]
	v_pk_fma_f32 v[14:15], v[6:7], v[2:3], v[110:111]
	global_store_dwordx4 v[48:49], v[12:15], off
	s_nop 0
	v_mov_b64_e32 v[0:1], v[120:121]
	v_mov_b64_e32 v[2:3], v[122:123]
	v_mov_b64_e32 v[4:5], v[124:125]
	v_mov_b64_e32 v[6:7], v[126:127]
	v_pk_mul_f32 v[0:1], v[0:1], v[8:9]
	v_pk_mul_f32 v[2:3], v[2:3], v[10:11]
	v_pk_fma_f32 v[8:9], v[4:5], v[0:1], v[104:105]
	v_pk_fma_f32 v[10:11], v[6:7], v[2:3], v[106:107]
	global_store_dwordx4 v[48:49], v[8:11], off offset:1024
	s_nop 0
	v_mov_b64_e32 v[0:1], v[128:129]
	v_mov_b64_e32 v[2:3], v[130:131]
	v_mov_b64_e32 v[4:5], v[132:133]
	v_mov_b64_e32 v[6:7], v[134:135]
	v_pk_mul_f32 v[0:1], v[0:1], v[78:79]
	v_pk_mul_f32 v[2:3], v[2:3], v[92:93]
	v_pk_fma_f32 v[4:5], v[4:5], v[0:1], v[100:101]
	v_pk_fma_f32 v[6:7], v[6:7], v[2:3], v[102:103]
	global_store_dwordx4 v[48:49], v[4:7], off offset:2048
	s_nop 0
	v_mov_b64_e32 v[0:1], v[136:137]
	v_mov_b64_e32 v[2:3], v[138:139]
	v_mov_b64_e32 v[92:93], v[140:141]
	v_mov_b64_e32 v[94:95], v[142:143]
	v_pk_mul_f32 v[78:79], v[88:89], v[40:41] op_sel_hi:[1,0]
	v_pk_mul_f32 v[88:89], v[90:91], v[40:41] op_sel_hi:[1,0]
	v_pk_mul_f32 v[0:1], v[78:79], v[0:1]
	v_pk_mul_f32 v[2:3], v[88:89], v[2:3]
	v_pk_fma_f32 v[0:1], v[92:93], v[0:1], v[96:97]
	v_pk_fma_f32 v[2:3], v[94:95], v[2:3], v[98:99]
	global_store_dwordx4 v[48:49], v[0:3], off offset:3072
	s_cbranch_vccnz .LBB0_325
	v_pk_mul_f32 v[78:79], v[12:13], v[12:13]
	v_pk_mul_f32 v[88:89], v[14:15], v[14:15]
	v_add_f32_e32 v17, v78, v79
	v_add_f32_e32 v17, v88, v17
	v_pk_mul_f32 v[90:91], v[8:9], v[8:9]
	v_add_f32_e32 v17, v89, v17
	v_add_f32_e32 v17, v90, v17
	v_pk_mul_f32 v[92:93], v[10:11], v[10:11]
	v_add_f32_e32 v17, v91, v17
	v_add_f32_e32 v17, v92, v17
	v_pk_mul_f32 v[94:95], v[4:5], v[4:5]
	v_add_f32_e32 v17, v93, v17
	v_add_f32_e32 v17, v94, v17
	v_pk_mul_f32 v[96:97], v[6:7], v[6:7]
	v_add_f32_e32 v17, v95, v17
	v_add_f32_e32 v17, v96, v17
	v_pk_mul_f32 v[98:99], v[0:1], v[0:1]
	v_add_f32_e32 v17, v97, v17
	v_add_f32_e32 v17, v98, v17
	v_add_f32_e32 v17, v99, v17
	v_mov_b64_e32 v[88:89], v[144:145]
	v_mov_b64_e32 v[90:91], v[146:147]
	v_mov_b64_e32 v[92:93], v[148:149]
	v_mov_b64_e32 v[94:95], v[150:151]
	v_mov_b64_e32 v[96:97], v[152:153]
	v_mov_b64_e32 v[98:99], v[154:155]
	v_pk_mul_f32 v[100:101], v[2:3], v[2:3]
	v_mov_b32_e32 v40, 0x358637bd
	v_add_f32_e32 v17, v100, v17
	v_add_f32_e32 v17, v101, v17
	s_nop 1
	v_add_f32_dpp v17, v17, v17 quad_perm:[1,0,3,2] row_mask:0xf bank_mask:0xf bound_ctrl:1
	s_nop 1
	v_add_f32_dpp v17, v17, v17 quad_perm:[2,3,0,1] row_mask:0xf bank_mask:0xf bound_ctrl:1
	s_nop 1
	v_add_f32_dpp v17, v17, v17 row_half_mirror row_mask:0xf bank_mask:0xf bound_ctrl:1
	s_nop 1
	v_add_f32_dpp v17, v17, v17 row_mirror row_mask:0xf bank_mask:0xf bound_ctrl:1
	s_nop 0
	v_readlane_b32 s14, v17, 16
	v_readlane_b32 s15, v17, 48
	v_readlane_b32 s12, v17, 0
	v_readlane_b32 s13, v17, 32
	v_mov_b32_e32 v78, s14
	v_mov_b32_e32 v79, s15
	v_pk_add_f32 v[78:79], s[12:13], v[78:79]
	s_nop 0
	v_add_f32_e32 v17, v78, v79
	v_fmamk_f32 v17, v17, 0x3a800000, v40
	v_cmp_gt_f32_e32 vcc, s70, v17
	v_mul_f32_e32 v40, 0x4b800000, v17
	v_pk_add_f32 v[78:79], v[96:97], 1.0 op_sel_hi:[1,0]
	v_cndmask_b32_e32 v17, v17, v40, vcc
	v_rsq_f32_e32 v17, v17
	s_nop 0
	v_mul_f32_e32 v40, 0x45800000, v17
	v_cndmask_b32_e32 v40, v17, v40, vcc
	v_pk_mul_f32 v[12:13], v[12:13], v[40:41] op_sel_hi:[1,0]
	v_pk_mul_f32 v[14:15], v[14:15], v[40:41] op_sel_hi:[1,0]
	v_pk_mul_f32 v[12:13], v[88:89], v[12:13]
	v_pk_mul_f32 v[14:15], v[90:91], v[14:15]
	v_pk_fma_f32 v[12:13], v[78:79], v[12:13], v[92:93]
	v_pk_add_f32 v[78:79], v[98:99], 1.0 op_sel_hi:[1,0]
	v_cvt_pk_f16_f32 v12, v12, v13
	v_pk_fma_f32 v[14:15], v[78:79], v[14:15], v[94:95]
	v_pk_mul_f32 v[8:9], v[8:9], v[40:41] op_sel_hi:[1,0]
	v_cvt_pk_f16_f32 v13, v14, v15
	global_store_dwordx2 v[46:47], v[12:13], off
	s_nop 0
	v_mov_b64_e32 v[12:13], v[156:157]
	v_mov_b64_e32 v[14:15], v[158:159]
	s_nop 0
	v_mov_b64_e32 v[88:89], v[160:161]
	v_mov_b64_e32 v[90:91], v[162:163]
	v_mov_b64_e32 v[92:93], v[164:165]
	v_mov_b64_e32 v[94:95], v[166:167]
	v_pk_mul_f32 v[10:11], v[10:11], v[40:41] op_sel_hi:[1,0]
	v_pk_mul_f32 v[4:5], v[4:5], v[40:41] op_sel_hi:[1,0]
	v_pk_mul_f32 v[6:7], v[6:7], v[40:41] op_sel_hi:[1,0]
	v_pk_mul_f32 v[0:1], v[0:1], v[40:41] op_sel_hi:[1,0]
	v_pk_mul_f32 v[2:3], v[2:3], v[40:41] op_sel_hi:[1,0]
	v_pk_mul_f32 v[8:9], v[12:13], v[8:9]
	v_pk_mul_f32 v[10:11], v[14:15], v[10:11]
	v_pk_add_f32 v[12:13], v[92:93], 1.0 op_sel_hi:[1,0]
	s_nop 0
	v_pk_fma_f32 v[8:9], v[12:13], v[8:9], v[88:89]
	v_pk_add_f32 v[12:13], v[94:95], 1.0 op_sel_hi:[1,0]
	v_cvt_pk_f16_f32 v8, v8, v9
	v_pk_fma_f32 v[10:11], v[12:13], v[10:11], v[90:91]
	s_nop 0
	v_cvt_pk_f16_f32 v9, v10, v11
	global_store_dwordx2 v[46:47], v[8:9], off offset:512
	s_nop 0
	v_mov_b64_e32 v[8:9], v[168:169]
	v_mov_b64_e32 v[10:11], v[170:171]
	s_nop 0
	v_mov_b64_e32 v[12:13], v[172:173]
	v_mov_b64_e32 v[14:15], v[174:175]
	v_mov_b64_e32 v[88:89], v[176:177]
	v_mov_b64_e32 v[90:91], v[178:179]
	v_pk_mul_f32 v[4:5], v[8:9], v[4:5]
	v_pk_mul_f32 v[6:7], v[10:11], v[6:7]
	v_pk_add_f32 v[8:9], v[88:89], 1.0 op_sel_hi:[1,0]
	s_nop 0
	v_pk_fma_f32 v[4:5], v[4:5], v[8:9], v[12:13]
	v_pk_add_f32 v[8:9], v[90:91], 1.0 op_sel_hi:[1,0]
	v_cvt_pk_f16_f32 v4, v4, v5
	v_pk_fma_f32 v[6:7], v[6:7], v[8:9], v[14:15]
	s_nop 0
	v_cvt_pk_f16_f32 v5, v6, v7
	global_store_dwordx2 v[46:47], v[4:5], off offset:1024
	s_nop 0
	v_mov_b64_e32 v[8:9], v[180:181]
	v_mov_b64_e32 v[10:11], v[182:183]
	s_nop 0
	v_mov_b64_e32 v[4:5], v[184:185]
	v_mov_b64_e32 v[6:7], v[186:187]
	v_mov_b64_e32 v[12:13], v[188:189]
	v_mov_b64_e32 v[14:15], v[190:191]
	v_pk_mul_f32 v[0:1], v[0:1], v[8:9]
	v_pk_mul_f32 v[2:3], v[2:3], v[10:11]
	v_pk_add_f32 v[8:9], v[12:13], 1.0 op_sel_hi:[1,0]
	s_nop 0
	v_pk_fma_f32 v[0:1], v[0:1], v[8:9], v[4:5]
	v_pk_add_f32 v[4:5], v[14:15], 1.0 op_sel_hi:[1,0]
	v_cvt_pk_f16_f32 v0, v0, v1
	v_pk_fma_f32 v[2:3], v[2:3], v[4:5], v[6:7]
	s_nop 0
	v_cvt_pk_f16_f32 v1, v2, v3
	global_store_dwordx2 v[46:47], v[0:1], off offset:1536
	s_branch .LBB0_325
